# P7a merged lgkm waits; P7c reduction deferred into next gather-issue block; gather address via v_mad_u32_u16 + saddr loads
# speedup vs baseline: 1.0428x; 1.0174x over previous
.LBB0_801:
	s_lshl_b32 s31, s28, 3
	s_add_i32 s23, s90, s31
	s_min_i32 s23, s23, 0x3ff
	s_lshl_b32 s84, s23, 12
	v_lshl_add_u64 v[228:229], v[178:179], 0, s[84:85]
	global_load_dwordx4 v[112:115], v[228:229], off
	global_load_dwordx4 v[116:119], v[228:229], off offset:1024
	s_waitcnt lgkmcnt(8)
	v_mfma_i32_16x16x64_i8 v[120:123], v[64:67], v[120:123], 0
	v_mfma_i32_16x16x64_i8 v[120:123], v[68:71], v[124:127], v[120:123]
	v_mfma_i32_16x16x64_i8 v[120:123], v[72:75], v[128:131], v[120:123]
	v_mfma_i32_16x16x64_i8 v[128:131], v[76:79], v[132:135], v[120:123]
	s_waitcnt lgkmcnt(4)
	v_mfma_i32_16x16x64_i8 v[120:123], v[64:67], v[136:139], 0
	v_mfma_i32_16x16x64_i8 v[120:123], v[68:71], v[140:143], v[120:123]
	v_mfma_i32_16x16x64_i8 v[120:123], v[72:75], v[144:147], v[120:123]
	v_mfma_i32_16x16x64_i8 v[132:135], v[76:79], v[148:151], v[120:123]
	s_nop 5
	global_load_dwordx4 v[120:123], v[228:229], off offset:2048
	global_load_dwordx4 v[124:127], v[228:229], off offset:3072
	v_and_b32_e32 v140, 0x20000, v215
	v_cmp_eq_u32_e32 vcc, 0, v140
	s_waitcnt lgkmcnt(0)
	v_mfma_i32_16x16x64_i8 v[136:139], v[64:67], v[152:155], 0
	v_cndmask_b32_e32 v128, v129, v128, vcc
	v_cndmask_b32_e32 v129, v131, v130, vcc
	v_and_b32_e32 v130, 0x40000, v215
	v_cmp_eq_u32_e32 vcc, 0, v130
	v_mfma_i32_16x16x64_i8 v[136:139], v[68:71], v[156:159], v[136:139]
	v_and_b32_e32 v130, 0x40000, v216
	v_cndmask_b32_e32 v128, v129, v128, vcc
	v_cvt_f32_i32_e32 v128, v128
	v_bfe_u32 v129, v215, 19, 2
	v_cmp_eq_u32_e32 vcc, v129, v210
	v_mfma_i32_16x16x64_i8 v[136:139], v[72:75], v[160:163], v[136:139]
	v_cndmask_b32_e32 v129, v212, v213, vcc
	ds_write_b32 v129, v128
	v_and_b32_e32 v128, 0x20000, v216
	v_cmp_eq_u32_e32 vcc, 0, v128
	v_mfma_i32_16x16x64_i8 v[136:139], v[76:79], v[164:167], v[136:139]
	v_cndmask_b32_e32 v128, v133, v132, vcc
	v_cndmask_b32_e32 v129, v135, v134, vcc
	v_cmp_eq_u32_e32 vcc, 0, v130
	s_nop 1
	v_cndmask_b32_e32 v128, v129, v128, vcc
	v_cvt_f32_i32_e32 v128, v128
	v_bfe_u32 v129, v216, 19, 2
	v_cmp_eq_u32_e32 vcc, v129, v210
	s_nop 1
	v_cndmask_b32_e32 v129, v212, v213, vcc
	ds_write_b32 v129, v128 offset:64
	s_mov_b32 s93, s85
	v_lshl_add_u64 v[128:129], s[92:93], 2, v[180:181]
	s_add_i32 s84, s92, 16
	global_load_dword v227, v[128:129], off
	v_lshl_add_u64 v[128:129], s[84:85], 2, v[180:181]
	global_load_dword v177, v[128:129], off
	v_and_b32_e32 v128, 0x20000, v220
	v_cmp_eq_u32_e32 vcc, 0, v128
	v_and_b32_e32 v130, 0x40000, v220
	s_nop 0
	v_cndmask_b32_e32 v128, v137, v136, vcc
	v_cndmask_b32_e32 v129, v139, v138, vcc
	v_cmp_eq_u32_e32 vcc, 0, v130
	s_nop 1
	v_cndmask_b32_e32 v128, v129, v128, vcc
	v_cvt_f32_i32_e32 v128, v128
	v_bfe_u32 v129, v220, 19, 2
	v_cmp_eq_u32_e32 vcc, v129, v210
	s_nop 1
	v_cndmask_b32_e32 v129, v212, v213, vcc
	s_andn2_b64 vcc, exec, s[0:1]
	ds_write_b32 v129, v128 offset:128
	s_cbranch_vccnz .LBB0_803
	v_mfma_i32_16x16x64_i8 v[4:7], v[64:67], v[4:7], 0
	s_waitcnt vmcnt(22)
	v_and_b32_e32 v128, 0x20000, v217
	v_cmp_eq_u32_e32 vcc, 0, v128
	v_and_b32_e32 v130, 0x40000, v217
	v_mfma_i32_16x16x64_i8 v[4:7], v[68:71], v[0:3], v[4:7]
	v_mfma_i32_16x16x64_i8 v[4:7], v[72:75], v[8:11], v[4:7]
	v_mfma_i32_16x16x64_i8 v[4:7], v[76:79], v[12:15], v[4:7]
	s_nop 7
	v_cndmask_b32_e32 v128, v5, v4, vcc
	v_cndmask_b32_e32 v129, v7, v6, vcc
	v_cmp_eq_u32_e32 vcc, 0, v130
	s_nop 1
	v_cndmask_b32_e32 v128, v129, v128, vcc
	v_cvt_f32_i32_e32 v128, v128
	v_bfe_u32 v129, v217, 19, 2
	v_cmp_eq_u32_e32 vcc, v129, v210
	s_nop 1
	v_cndmask_b32_e32 v129, v212, v213, vcc
	ds_write_b32 v129, v128 offset:192

.LBB0_810:
	s_add_i32 s23, s54, s31
	s_min_i32 s23, s23, 0x3ff
	s_lshl_b32 s84, s23, 12
	v_lshl_add_u64 v[216:217], v[178:179], 0, s[84:85]
	global_load_dwordx4 v[64:67], v[216:217], off
	global_load_dwordx4 v[68:71], v[216:217], off offset:1024
	s_waitcnt lgkmcnt(8)
	v_mfma_i32_16x16x64_i8 v[72:75], v[80:83], v[72:75], 0
	v_mfma_i32_16x16x64_i8 v[72:75], v[84:87], v[76:79], v[72:75]
	v_mfma_i32_16x16x64_i8 v[72:75], v[88:91], v[128:131], v[72:75]
	v_mfma_i32_16x16x64_i8 v[128:131], v[92:95], v[148:151], v[72:75]
	s_waitcnt lgkmcnt(4)
	v_mfma_i32_16x16x64_i8 v[72:75], v[80:83], v[152:155], 0
	v_mfma_i32_16x16x64_i8 v[72:75], v[84:87], v[156:159], v[72:75]
	v_mfma_i32_16x16x64_i8 v[72:75], v[88:91], v[160:163], v[72:75]
	v_mfma_i32_16x16x64_i8 v[148:151], v[92:95], v[164:167], v[72:75]
	s_nop 5
	global_load_dwordx4 v[72:75], v[216:217], off offset:2048
	global_load_dwordx4 v[76:79], v[216:217], off offset:3072
	s_waitcnt lgkmcnt(0)
	v_mfma_i32_16x16x64_i8 v[132:135], v[80:83], v[132:135], 0
	v_mfma_i32_16x16x64_i8 v[132:135], v[84:87], v[136:139], v[132:135]
	v_and_b32_e32 v136, 0x20000, v218
	v_cmp_eq_u32_e32 vcc, 0, v136
	v_mfma_i32_16x16x64_i8 v[132:135], v[88:91], v[140:143], v[132:135]
	v_cndmask_b32_e32 v128, v129, v128, vcc
	v_cndmask_b32_e32 v129, v131, v130, vcc
	v_and_b32_e32 v130, 0x40000, v218
	v_cmp_eq_u32_e32 vcc, 0, v130
	v_and_b32_e32 v130, 0x40000, v219
	v_mfma_i32_16x16x64_i8 v[132:135], v[92:95], v[144:147], v[132:135]
	v_cndmask_b32_e32 v128, v129, v128, vcc
	v_cvt_f32_i32_e32 v128, v128
	v_bfe_u32 v129, v218, 19, 2
	v_cmp_eq_u32_e32 vcc, v129, v210
	s_nop 1
	v_cndmask_b32_e32 v129, v212, v213, vcc
	ds_write_b32 v129, v128
	v_and_b32_e32 v128, 0x20000, v219
	v_cmp_eq_u32_e32 vcc, 0, v128
	s_nop 1
	v_cndmask_b32_e32 v128, v149, v148, vcc
	v_cndmask_b32_e32 v129, v151, v150, vcc
	v_cmp_eq_u32_e32 vcc, 0, v130
	s_nop 1
	v_cndmask_b32_e32 v128, v129, v128, vcc
	v_cvt_f32_i32_e32 v128, v128
	v_bfe_u32 v129, v219, 19, 2
	v_cmp_eq_u32_e32 vcc, v129, v210
	s_nop 1
	v_cndmask_b32_e32 v129, v212, v213, vcc
	ds_write_b32 v129, v128 offset:64
	s_mov_b32 s23, s85
	v_lshl_add_u64 v[128:129], s[22:23], 2, v[180:181]
	s_add_i32 s84, s22, 16
	global_load_dword v215, v[128:129], off
	v_lshl_add_u64 v[128:129], s[84:85], 2, v[180:181]
	global_load_dword v216, v[128:129], off
	v_and_b32_e32 v128, 0x20000, v224
	v_cmp_eq_u32_e32 vcc, 0, v128
	v_and_b32_e32 v130, 0x40000, v224
	s_nop 0
	v_cndmask_b32_e32 v128, v133, v132, vcc
	v_cndmask_b32_e32 v129, v135, v134, vcc
	v_cmp_eq_u32_e32 vcc, 0, v130
	s_nop 1
	v_cndmask_b32_e32 v128, v129, v128, vcc
	v_cvt_f32_i32_e32 v128, v128
	v_bfe_u32 v129, v224, 19, 2
	v_cmp_eq_u32_e32 vcc, v129, v210
	s_nop 1
	v_cndmask_b32_e32 v129, v212, v213, vcc
	s_andn2_b64 vcc, exec, s[0:1]
	ds_write_b32 v129, v128 offset:128
	s_cbranch_vccnz .LBB0_812
	v_mfma_i32_16x16x64_i8 v[20:23], v[80:83], v[20:23], 0
	s_waitcnt vmcnt(23)
	v_and_b32_e32 v128, 0x20000, v221
	v_cmp_eq_u32_e32 vcc, 0, v128
	v_and_b32_e32 v130, 0x40000, v221
	v_mfma_i32_16x16x64_i8 v[20:23], v[84:87], v[16:19], v[20:23]
	v_mfma_i32_16x16x64_i8 v[20:23], v[88:91], v[24:27], v[20:23]
	v_mfma_i32_16x16x64_i8 v[20:23], v[92:95], v[32:35], v[20:23]
	s_nop 7
	v_cndmask_b32_e32 v128, v21, v20, vcc
	v_cndmask_b32_e32 v129, v23, v22, vcc
	v_cmp_eq_u32_e32 vcc, 0, v130
	s_nop 1
	v_cndmask_b32_e32 v128, v129, v128, vcc
	v_cvt_f32_i32_e32 v128, v128
	v_bfe_u32 v129, v221, 19, 2
	v_cmp_eq_u32_e32 vcc, v129, v210
	s_nop 1
	v_cndmask_b32_e32 v129, v212, v213, vcc
	ds_write_b32 v129, v128 offset:192

.LBB0_819:
	s_lshl_b32 s84, s21, 12
	v_lshl_add_u64 v[218:219], v[178:179], 0, s[84:85]
	global_load_dwordx4 v[80:83], v[218:219], off
	global_load_dwordx4 v[84:87], v[218:219], off offset:1024
	s_waitcnt lgkmcnt(8)
	v_mfma_i32_16x16x64_i8 v[88:91], v[96:99], v[88:91], 0
	v_mfma_i32_16x16x64_i8 v[88:91], v[100:103], v[92:95], v[88:91]
	v_mfma_i32_16x16x64_i8 v[88:91], v[104:107], v[128:131], v[88:91]
	v_mfma_i32_16x16x64_i8 v[128:131], v[108:111], v[148:151], v[88:91]
	s_waitcnt lgkmcnt(4)
	v_mfma_i32_16x16x64_i8 v[88:91], v[96:99], v[152:155], 0
	v_mfma_i32_16x16x64_i8 v[88:91], v[100:103], v[156:159], v[88:91]
	v_mfma_i32_16x16x64_i8 v[88:91], v[104:107], v[160:163], v[88:91]
	v_mfma_i32_16x16x64_i8 v[148:151], v[108:111], v[164:167], v[88:91]
	s_nop 5
	global_load_dwordx4 v[88:91], v[218:219], off offset:2048
	global_load_dwordx4 v[92:95], v[218:219], off offset:3072
	s_waitcnt lgkmcnt(0)
	v_mfma_i32_16x16x64_i8 v[132:135], v[96:99], v[132:135], 0
	v_mfma_i32_16x16x64_i8 v[132:135], v[100:103], v[136:139], v[132:135]
	v_and_b32_e32 v136, 0x20000, v222
	v_cmp_eq_u32_e32 vcc, 0, v136
	v_mfma_i32_16x16x64_i8 v[132:135], v[104:107], v[140:143], v[132:135]
	v_cndmask_b32_e32 v128, v129, v128, vcc
	v_cndmask_b32_e32 v129, v131, v130, vcc
	v_and_b32_e32 v130, 0x40000, v222
	v_cmp_eq_u32_e32 vcc, 0, v130
	v_and_b32_e32 v130, 0x40000, v223
	v_mfma_i32_16x16x64_i8 v[132:135], v[108:111], v[144:147], v[132:135]
	v_cndmask_b32_e32 v128, v129, v128, vcc
	v_cvt_f32_i32_e32 v128, v128
	v_bfe_u32 v129, v222, 19, 2
	v_cmp_eq_u32_e32 vcc, v129, v210
	s_nop 1
	v_cndmask_b32_e32 v129, v212, v213, vcc
	ds_write_b32 v129, v128
	v_and_b32_e32 v128, 0x20000, v223
	v_cmp_eq_u32_e32 vcc, 0, v128
	s_nop 1
	v_cndmask_b32_e32 v128, v149, v148, vcc
	v_cndmask_b32_e32 v129, v151, v150, vcc
	v_cmp_eq_u32_e32 vcc, 0, v130
	s_nop 1
	v_cndmask_b32_e32 v128, v129, v128, vcc
	v_cvt_f32_i32_e32 v128, v128
	v_bfe_u32 v129, v223, 19, 2
	v_cmp_eq_u32_e32 vcc, v129, v210
	s_nop 1
	v_cndmask_b32_e32 v129, v212, v213, vcc
	ds_write_b32 v129, v128 offset:64
	s_mov_b32 s81, s85
	v_lshl_add_u64 v[128:129], s[80:81], 2, v[180:181]
	s_add_i32 s84, s80, 16
	global_load_dword v218, v[128:129], off
	v_lshl_add_u64 v[128:129], s[84:85], 2, v[180:181]
	global_load_dword v219, v[128:129], off
	v_and_b32_e32 v128, 0x20000, v226
	v_cmp_eq_u32_e32 vcc, 0, v128
	v_and_b32_e32 v130, 0x40000, v226
	s_nop 0
	v_cndmask_b32_e32 v128, v133, v132, vcc
	v_cndmask_b32_e32 v129, v135, v134, vcc
	v_cmp_eq_u32_e32 vcc, 0, v130
	s_nop 1
	v_cndmask_b32_e32 v128, v129, v128, vcc
	v_cvt_f32_i32_e32 v128, v128
	v_bfe_u32 v129, v226, 19, 2
	v_cmp_eq_u32_e32 vcc, v129, v210
	s_nop 1
	v_cndmask_b32_e32 v129, v212, v213, vcc
	s_andn2_b64 vcc, exec, s[0:1]
	ds_write_b32 v129, v128 offset:128
	s_cbranch_vccnz .LBB0_821
	v_mfma_i32_16x16x64_i8 v[44:47], v[96:99], v[44:47], 0
	s_waitcnt vmcnt(24)
	v_and_b32_e32 v128, 0x20000, v225
	v_cmp_eq_u32_e32 vcc, 0, v128
	v_and_b32_e32 v130, 0x40000, v225
	v_mfma_i32_16x16x64_i8 v[44:47], v[100:103], v[48:51], v[44:47]
	v_mfma_i32_16x16x64_i8 v[44:47], v[104:107], v[56:59], v[44:47]
	v_mfma_i32_16x16x64_i8 v[44:47], v[108:111], v[60:63], v[44:47]
	s_nop 7
	v_cndmask_b32_e32 v128, v45, v44, vcc
	v_cndmask_b32_e32 v129, v47, v46, vcc
	v_cmp_eq_u32_e32 vcc, 0, v130
	s_nop 1
	v_cndmask_b32_e32 v128, v129, v128, vcc
	v_cvt_f32_i32_e32 v128, v128
	v_bfe_u32 v129, v225, 19, 2
	v_cmp_eq_u32_e32 vcc, v129, v210
	s_nop 1
	v_cndmask_b32_e32 v129, v212, v213, vcc
	ds_write_b32 v129, v128 offset:192

.LBB0_828:
	s_lshl_b32 s84, s23, 12
	v_lshl_add_u64 v[222:223], v[178:179], 0, s[84:85]
	global_load_dwordx4 v[96:99], v[222:223], off
	global_load_dwordx4 v[100:103], v[222:223], off offset:1024
	s_waitcnt lgkmcnt(8)
	v_mfma_i32_16x16x64_i8 v[104:107], v[112:115], v[104:107], 0
	v_mfma_i32_16x16x64_i8 v[104:107], v[116:119], v[108:111], v[104:107]
	v_mfma_i32_16x16x64_i8 v[104:107], v[120:123], v[128:131], v[104:107]
	v_mfma_i32_16x16x64_i8 v[128:131], v[124:127], v[148:151], v[104:107]
	s_waitcnt lgkmcnt(4)
	v_mfma_i32_16x16x64_i8 v[104:107], v[112:115], v[152:155], 0
	v_mfma_i32_16x16x64_i8 v[104:107], v[116:119], v[156:159], v[104:107]
	v_mfma_i32_16x16x64_i8 v[104:107], v[120:123], v[160:163], v[104:107]
	v_mfma_i32_16x16x64_i8 v[148:151], v[124:127], v[164:167], v[104:107]
	s_nop 5
	global_load_dwordx4 v[104:107], v[222:223], off offset:2048
	global_load_dwordx4 v[108:111], v[222:223], off offset:3072
	s_waitcnt lgkmcnt(0)
	v_mfma_i32_16x16x64_i8 v[132:135], v[112:115], v[132:135], 0
	v_mfma_i32_16x16x64_i8 v[132:135], v[116:119], v[136:139], v[132:135]
	v_and_b32_e32 v136, 0x20000, v227
	v_cmp_eq_u32_e32 vcc, 0, v136
	v_mfma_i32_16x16x64_i8 v[132:135], v[120:123], v[140:143], v[132:135]
	v_cndmask_b32_e32 v128, v129, v128, vcc
	v_cndmask_b32_e32 v129, v131, v130, vcc
	v_and_b32_e32 v130, 0x40000, v227
	v_cmp_eq_u32_e32 vcc, 0, v130
	v_and_b32_e32 v130, 0x40000, v177
	v_mfma_i32_16x16x64_i8 v[132:135], v[124:127], v[144:147], v[132:135]
	v_cndmask_b32_e32 v128, v129, v128, vcc
	v_cvt_f32_i32_e32 v128, v128
	v_bfe_u32 v129, v227, 19, 2
	v_cmp_eq_u32_e32 vcc, v129, v210
	s_nop 1
	v_cndmask_b32_e32 v129, v212, v213, vcc
	ds_write_b32 v129, v128
	v_and_b32_e32 v128, 0x20000, v177
	v_cmp_eq_u32_e32 vcc, 0, v128
	s_nop 1
	v_cndmask_b32_e32 v128, v149, v148, vcc
	v_cndmask_b32_e32 v129, v151, v150, vcc
	v_cmp_eq_u32_e32 vcc, 0, v130
	s_nop 1
	v_cndmask_b32_e32 v128, v129, v128, vcc
	v_cvt_f32_i32_e32 v128, v128
	v_bfe_u32 v129, v177, 19, 2
	v_cmp_eq_u32_e32 vcc, v129, v210
	s_nop 1
	v_cndmask_b32_e32 v129, v212, v213, vcc
	ds_write_b32 v129, v128 offset:64
	s_mov_b32 s21, s85
	v_lshl_add_u64 v[128:129], s[20:21], 2, v[180:181]
	s_add_i32 s84, s20, 16
	global_load_dword v222, v[128:129], off
	v_lshl_add_u64 v[128:129], s[84:85], 2, v[180:181]
	global_load_dword v223, v[128:129], off
	v_and_b32_e32 v128, 0x20000, v229
	v_cmp_eq_u32_e32 vcc, 0, v128
	v_and_b32_e32 v130, 0x40000, v229
	s_nop 0
	v_cndmask_b32_e32 v128, v133, v132, vcc
	v_cndmask_b32_e32 v129, v135, v134, vcc
	v_cmp_eq_u32_e32 vcc, 0, v130
	s_nop 1
	v_cndmask_b32_e32 v128, v129, v128, vcc
	v_cvt_f32_i32_e32 v128, v128
	v_bfe_u32 v129, v229, 19, 2
	v_cmp_eq_u32_e32 vcc, v129, v210
	s_nop 1
	v_cndmask_b32_e32 v129, v212, v213, vcc
	s_andn2_b64 vcc, exec, s[0:1]
	ds_write_b32 v129, v128 offset:128
	s_cbranch_vccnz .LBB0_830
	v_mfma_i32_16x16x64_i8 v[52:55], v[112:115], v[52:55], 0
	s_waitcnt vmcnt(25)
	v_and_b32_e32 v128, 0x20000, v228
	v_cmp_eq_u32_e32 vcc, 0, v128
	v_and_b32_e32 v130, 0x40000, v228
	v_mfma_i32_16x16x64_i8 v[52:55], v[116:119], v[40:43], v[52:55]
	v_mfma_i32_16x16x64_i8 v[52:55], v[120:123], v[36:39], v[52:55]
	v_mfma_i32_16x16x64_i8 v[52:55], v[124:127], v[28:31], v[52:55]
	s_nop 7
	v_cndmask_b32_e32 v128, v53, v52, vcc
	v_cndmask_b32_e32 v129, v55, v54, vcc
	v_cmp_eq_u32_e32 vcc, 0, v130
	s_nop 1
	v_cndmask_b32_e32 v128, v129, v128, vcc
	v_cvt_f32_i32_e32 v128, v128
	v_bfe_u32 v129, v228, 19, 2
	v_cmp_eq_u32_e32 vcc, v129, v210
	s_nop 1
	v_cndmask_b32_e32 v129, v212, v213, vcc
	ds_write_b32 v129, v128 offset:192

; #define P7C_LOADA(R0, R1, C, S, X, t) do { const int tt_ = (t) < NT_TOK ? (t) : NT_TOK - 1; const unsigned char* rp_ = rp0 + (size_t)tt_ * 256; R0 = *(const v4u*)rp_; R1 = *(const v4u*)(rp_ + 16); \
;             C = *(const v4u*)(cp0 + (size_t)tt_ * 128); S = SCQ[tt_]; X = *(const unsigned*)(X2Bw + (size_t)tt_ * DM + 128 * hs + 16 * seg + 2 * r); } while (0)
; #define P7C_ISSUE(G, R0, R1) do { __builtin_amdgcn_s_setprio(3); _Pragma("unroll") for (int i_ = 0; i_ < 16; ++i_) { const unsigned e_ = P7_EID(R0, R1, i_); G[i_] = *(const v4u*)(Vb + (size_t)e_ * 128); } __builtin_amdgcn_s_setprio(0); } while (0)
; __device__ __forceinline__ void p7c_vaxpy(Frame& F, unsigned* bar, unsigned x, unsigned rank) {
;     ...
;     for (int pass = 0; pass < 16; ++pass) {
;         const int hs = (2 * (int)so.vx + pass) & 15; if ((unsigned)(hs >> 1) % so.npop != so.vx) continue;
;         const unsigned char* Vb = F.ws + WS_V + (size_t)hs * (16384 * 128) + 16 * seg;
;         const unsigned char* rp0 = RE16b + r * 32; const unsigned char* cp0 = CQb + r * 16;
;     ...
;         v4u GA[16], GB[16], ra0, ra1, ca, rb0, rb1, cb, cA, cB; float sa, sb, sA, sB; unsigned xa, xb2, xA, xB;
;         P7C_LOADA(ra0, ra1, ca, sa, xa, gwl);
;         P7C_LOADA(rb0, rb1, cb, sb, xb2, gwl + stride);
;         P7C_ISSUE(GA, ra0, ra1); cA = ca; sA = sa; xA = xa;
.LBB0_1084:
	s_waitcnt vmcnt(23)
	v_add_u32_e32 v0, s22, v192
	v_bfe_u32 v1, v0, 1, 3
	v_mul_hi_u32 v2, v1, v193
	v_mul_lo_u32 v2, v2, v191
	v_sub_u32_e32 v1, v1, v2
	v_sub_u32_e32 v2, v1, v191
	v_cmp_ge_u32_e32 vcc, v1, v191
	s_nop 1
	v_cndmask_b32_e32 v1, v1, v2, vcc
	v_sub_u32_e32 v2, v1, v191
	v_cmp_ge_u32_e32 vcc, v1, v191
	s_nop 1
	v_cndmask_b32_e32 v1, v1, v2, vcc
	v_cmp_ne_u32_e32 vcc, v1, v190
	s_cbranch_vccnz .LBB0_1083
	v_and_b32_e32 v80, 15, v0
	v_lshlrev_b32_e32 v156, 21, v80
	v_lshl_add_u64 v[180:181], v[176:177], 0, v[156:157]
	s_nop 1
	v_readfirstlane_b32 s56, v180
	v_readfirstlane_b32 s57, v181
	s_movk_i32 s58, 0x80
	s_nop 3
	s_sub_u32 s56, s56, 0x80
	s_subb_u32 s57, s57, 0
	s_nop 3
	v_subrev_u32_e32 v200, s56, v180
	v_lshlrev_b32_e32 v156, 8, v80
	global_load_dwordx4 v[24:27], v[162:163], off offset:16
	global_load_dwordx4 v[8:11], v[162:163], off
	s_waitcnt vmcnt(4)
	v_lshl_add_u64 v[12:13], v[166:167], 0, v[156:157]
	global_load_dwordx4 v[0:3], v[164:165], off
	global_load_dwordx4 v[76:79], v[168:169], off
	global_load_dwordx4 v[64:67], v[168:169], off offset:16
	global_load_dwordx4 v[4:7], v[170:171], off
	v_lshl_add_u64 v[14:15], v[172:173], 0, v[156:157]
	global_load_dword v196, v157, s[4:5]
	global_load_dword v197, v[12:13], off
	global_load_dword v198, v157, s[6:7]
	global_load_dword v199, v[14:15], off
	s_setprio 3
	s_waitcnt vmcnt(8)
	v_mad_u32_u16 v12, v8, s58, v200 op_sel:[0,0,0,0]
	v_mad_u32_u16 v14, v8, s58, v200 op_sel:[1,0,0,0]
	global_load_dwordx4 v[48:51], v12, s[56:57]
	global_load_dwordx4 v[52:55], v14, s[56:57]
	v_mad_u32_u16 v12, v9, s58, v200 op_sel:[0,0,0,0]
	v_mad_u32_u16 v8, v9, s58, v200 op_sel:[1,0,0,0]
	global_load_dwordx4 v[68:71], v12, s[56:57]
	global_load_dwordx4 v[72:75], v8, s[56:57]
	v_mad_u32_u16 v8, v10, s58, v200 op_sel:[0,0,0,0]
	v_mad_u32_u16 v12, v10, s58, v200 op_sel:[1,0,0,0]
	global_load_dwordx4 v[32:35], v8, s[56:57]
	global_load_dwordx4 v[36:39], v12, s[56:57]
	v_mad_u32_u16 v8, v11, s58, v200 op_sel:[0,0,0,0]
	v_mad_u32_u16 v10, v11, s58, v200 op_sel:[1,0,0,0]
	global_load_dwordx4 v[56:59], v8, s[56:57]
	global_load_dwordx4 v[60:63], v10, s[56:57]
	v_mad_u32_u16 v8, v24, s58, v200 op_sel:[0,0,0,0]
	v_mad_u32_u16 v10, v24, s58, v200 op_sel:[1,0,0,0]
	global_load_dwordx4 v[16:19], v8, s[56:57]
	global_load_dwordx4 v[20:23], v10, s[56:57]
	v_mad_u32_u16 v8, v25, s58, v200 op_sel:[0,0,0,0]
	v_mad_u32_u16 v10, v25, s58, v200 op_sel:[1,0,0,0]
	global_load_dwordx4 v[40:43], v8, s[56:57]
	global_load_dwordx4 v[44:47], v10, s[56:57]
	v_mad_u32_u16 v8, v26, s58, v200 op_sel:[0,0,0,0]
	v_mad_u32_u16 v12, v26, s58, v200 op_sel:[1,0,0,0]
	v_mad_u32_u16 v24, v27, s58, v200 op_sel:[0,0,0,0]
	v_mad_u32_u16 v28, v27, s58, v200 op_sel:[1,0,0,0]
	global_load_dwordx4 v[8:11], v8, s[56:57]
	s_nop 0
	global_load_dwordx4 v[12:15], v12, s[56:57]
	s_nop 0
	global_load_dwordx4 v[24:27], v24, s[56:57]
	s_nop 0
	global_load_dwordx4 v[28:31], v28, s[56:57]
	s_setprio 0
	s_andn2_b64 vcc, exec, s[8:9]
	s_cbranch_vccnz .LBB0_1083
	v_lshlrev_b32_e32 v81, 7, v80
	v_lshlrev_b32_e32 v156, 1, v81
	v_lshl_add_u64 v[182:183], v[174:175], 0, v[156:157]
	v_lshlrev_b32_e32 v156, 2, v80
	v_and_b32_e32 v80, 15, v195
	v_lshl_add_u64 v[184:185], s[2:3], 0, v[156:157]
	v_lshlrev_b32_e32 v156, 2, v80
	v_lshl_add_u64 v[186:187], s[12:13], 0, v[156:157]
	v_lshlrev_b32_e32 v156, 8, v80
	v_lshl_add_u64 v[188:189], v[178:179], 0, v[156:157]
	s_mov_b32 s20, s0
	s_mov_b32 s98, 0x7fffffff
	s_branch .LBB0_1089

; #define P7C_LOADA(R0, R1, C, S, X, t) do { const int tt_ = (t) < NT_TOK ? (t) : NT_TOK - 1; const unsigned char* rp_ = rp0 + (size_t)tt_ * 256; R0 = *(const v4u*)rp_; R1 = *(const v4u*)(rp_ + 16); \
;             C = *(const v4u*)(cp0 + (size_t)tt_ * 128); S = SCQ[tt_]; X = *(const unsigned*)(X2Bw + (size_t)tt_ * DM + 128 * hs + 16 * seg + 2 * r); } while (0)
; #define P7C_ISSUE(G, R0, R1) do { __builtin_amdgcn_s_setprio(3); _Pragma("unroll") for (int i_ = 0; i_ < 16; ++i_) { const unsigned e_ = P7_EID(R0, R1, i_); G[i_] = *(const v4u*)(Vb + (size_t)e_ * 128); } __builtin_amdgcn_s_setprio(0); } while (0)
; __device__ __forceinline__ void p7c_vaxpy(Frame& F, unsigned* bar, unsigned x, unsigned rank) {
;     ...
;         v4u GA[16], GB[16], ra0, ra1, ca, rb0, rb1, cb, cA, cB; float sa, sb, sA, sB; unsigned xa, xb2, xA, xB;
;         P7C_LOADA(ra0, ra1, ca, sa, xa, gwl);
;         P7C_LOADA(rb0, rb1, cb, sb, xb2, gwl + stride);
;         P7C_ISSUE(GA, ra0, ra1); cA = ca; sA = sa; xA = xa;
; #pragma unroll 1
;         for (int t = gwl; t < NT_TOK; t += 2 * stride) {
;             P7C_LOADA(ra0, ra1, ca, sa, xa, t + 2 * stride); P7C_ISSUE(GB, rb0, rb1); cB = cb; sB = sb; xB = xb2; P7C_COMP(GA, cA, sA, xA, t);
;             P7C_LOADA(rb0, rb1, cb, sb, xb2, t + 3 * stride); P7C_ISSUE(GA, ra0, ra1); cA = ca; sA = sa; xA = xa; P7C_COMP(GB, cB, sB, xB, t + stride);
.LBB0_1089:
	s_add_i32 s27, s20, s10
	s_min_i32 s18, s27, 0x5fff
	s_ashr_i32 s19, s18, 31
	s_waitcnt vmcnt(23)
	v_mov_b64_e32 v[154:155], v[2:3]
	s_lshl_b64 s[28:29], s[18:19], 8
	v_mov_b64_e32 v[152:153], v[0:1]
	v_lshl_add_u64 v[0:1], v[158:159], 0, s[28:29]
	s_lshl_b64 s[28:29], s[18:19], 7
	global_load_dwordx4 v[144:147], v[0:1], off offset:16
	global_load_dwordx4 v[148:151], v[0:1], off
	v_lshl_add_u64 v[0:1], v[160:161], 0, s[28:29]
	s_lshl_b64 s[28:29], s[18:19], 2
	s_add_u32 s28, s54, s28
	s_addc_u32 s29, s55, s29
	s_lshl_b64 s[18:19], s[18:19], 12
	s_waitcnt vmcnt(20)
	v_mov_b32_e32 v206, v197
	v_mov_b32_e32 v207, v196
	v_lshl_add_u64 v[80:81], v[182:183], 0, s[18:19]
	global_load_dwordx4 v[0:3], v[0:1], off
	s_nop 0
	global_load_dword v196, v157, s[28:29]
	global_load_dword v197, v[80:81], off
	s_setprio 3
	v_permlane32_swap_b32_e32 v232, v236
	v_permlane32_swap_b32_e32 v233, v237
	v_mad_u32_u16 v80, v76, s58, v200 op_sel:[0,0,0,0]
	v_permlane32_swap_b32_e32 v234, v238
	v_permlane32_swap_b32_e32 v235, v239
	v_mad_u32_u16 v82, v76, s58, v200 op_sel:[1,0,0,0]
	v_add_u32_e32 v232, v232, v236
	v_add_u32_e32 v233, v233, v237
	global_load_dwordx4 v[128:131], v80, s[56:57]
	v_add_u32_e32 v234, v234, v238
	global_load_dwordx4 v[132:135], v82, s[56:57]
	v_add_u32_e32 v235, v235, v239
	v_mad_u32_u16 v80, v77, s58, v200 op_sel:[0,0,0,0]
	s_nop 1
	v_permlane16_swap_b32_e32 v232, v234
	v_mad_u32_u16 v76, v77, s58, v200 op_sel:[1,0,0,0]
	v_permlane16_swap_b32_e32 v233, v235
	global_load_dwordx4 v[136:139], v80, s[56:57]
	v_add_u32_e32 v232, v232, v234
	global_load_dwordx4 v[140:143], v76, s[56:57]
	v_add_u32_e32 v233, v233, v235
	s_nop 1
	v_mad_u32_u16 v76, v78, s58, v200 op_sel:[0,0,0,0]
	v_mov_b32_dpp v234, v232 quad_perm:[1,0,3,2] row_mask:0xf bank_mask:0xf
	v_mov_b32_dpp v235, v233 quad_perm:[1,0,3,2] row_mask:0xf bank_mask:0xf
	v_mad_u32_u16 v80, v78, s58, v200 op_sel:[1,0,0,0]
	v_cndmask_b32_e64 v236, v235, v232, s[44:45]
	global_load_dwordx4 v[112:115], v76, s[56:57]
	v_cndmask_b32_e64 v237, v233, v234, s[44:45]
	global_load_dwordx4 v[116:119], v80, s[56:57]
	v_cvt_f32_i32_e32 v236, v236
	v_cvt_f32_i32_e32 v237, v237
	v_mad_u32_u16 v76, v79, s58, v200 op_sel:[0,0,0,0]
	v_lshlrev_b32_e32 v238, 16, v204
	v_and_b32_e32 v239, 0xffff0000, v204
	v_mad_u32_u16 v78, v79, s58, v200 op_sel:[1,0,0,0]
	v_fmac_f32_e32 v238, v205, v236
	global_load_dwordx4 v[120:123], v76, s[56:57]
	v_fmac_f32_e32 v239, v205, v237
	global_load_dwordx4 v[124:127], v78, s[56:57]
	v_mul_f32_e32 v240, v239, v239
	v_fmac_f32_e32 v240, v238, v238
	v_mad_u32_u16 v76, v64, s58, v200 op_sel:[0,0,0,0]
	v_cvt_pk_bf16_f32 v244, v238, v239
	s_cmpk_gt_i32 s98, 0x5fff
	s_cbranch_scc1 .Lp7c_sk1_b
	s_ashr_i32 s99, s98, 31
	s_lshl_b64 s[100:101], s[98:99], 12
	v_lshl_add_u64 v[242:243], v[182:183], 0, s[100:101]
	global_store_dword v[242:243], v244, off
.Lp7c_sk1_b:
	v_mad_u32_u16 v78, v64, s58, v200 op_sel:[1,0,0,0]
	s_nop 1
	v_add_f32_dpp v240, v240, v240 quad_perm:[1,0,3,2] row_mask:0xf bank_mask:0xf
	global_load_dwordx4 v[96:99], v76, s[56:57]
	s_nop 1
	global_load_dwordx4 v[100:103], v78, s[56:57]
	v_add_f32_dpp v240, v240, v240 quad_perm:[2,3,0,1] row_mask:0xf bank_mask:0xf
	v_mad_u32_u16 v76, v65, s58, v200 op_sel:[0,0,0,0]
	s_nop 1
	v_add_f32_dpp v240, v240, v240 row_half_mirror row_mask:0xf bank_mask:0xf
	v_mad_u32_u16 v64, v65, s58, v200 op_sel:[1,0,0,0]
	s_nop 1
	global_load_dwordx4 v[104:107], v76, s[56:57]
	v_add_f32_dpp v240, v240, v240 row_mirror row_mask:0xf bank_mask:0xf
	global_load_dwordx4 v[108:111], v64, s[56:57]
	v_mov_b32_e32 v242, v240
	s_nop 1
	v_mad_u32_u16 v64, v66, s58, v200 op_sel:[0,0,0,0]
	v_permlane16_swap_b32_e32 v240, v242
	v_add_f32_e32 v240, v240, v242
	v_mad_u32_u16 v76, v66, s58, v200 op_sel:[1,0,0,0]
	v_mov_b32_e32 v242, v240
	global_load_dwordx4 v[80:83], v64, s[56:57]
	s_nop 1
	global_load_dwordx4 v[84:87], v76, s[56:57]
	v_permlane32_swap_b32_e32 v240, v242
	v_add_f32_e32 v240, v240, v242
	v_mad_u32_u16 v64, v67, s58, v200 op_sel:[0,0,0,0]
	s_cmpk_gt_i32 s98, 0x5fff
	s_cbranch_scc1 .Lp7c_sk2_b
	s_ashr_i32 s99, s98, 31
	s_lshl_b64 s[100:101], s[98:99], 6
	v_lshl_add_u64 v[242:243], v[184:185], 0, s[100:101]
	s_and_saveexec_b64 s[18:19], s[42:43]
	global_store_dword v[242:243], v240, off
	s_mov_b64 exec, s[18:19]
; #define P7C_LOADA(R0, R1, C, S, X, t) do { const int tt_ = (t) < NT_TOK ? (t) : NT_TOK - 1; const unsigned char* rp_ = rp0 + (size_t)tt_ * 256; R0 = *(const v4u*)rp_; R1 = *(const v4u*)(rp_ + 16); \
;             C = *(const v4u*)(cp0 + (size_t)tt_ * 128); S = SCQ[tt_]; X = *(const unsigned*)(X2Bw + (size_t)tt_ * DM + 128 * hs + 16 * seg + 2 * r); } while (0)
; #define P7C_ISSUE(G, R0, R1) do { __builtin_amdgcn_s_setprio(3); _Pragma("unroll") for (int i_ = 0; i_ < 16; ++i_) { const unsigned e_ = P7_EID(R0, R1, i_); G[i_] = *(const v4u*)(Vb + (size_t)e_ * 128); } __builtin_amdgcn_s_setprio(0); } while (0)
; __device__ __forceinline__ void p7c_vaxpy(Frame& F, unsigned* bar, unsigned x, unsigned rank) {
;     ...
;         v4u GA[16], GB[16], ra0, ra1, ca, rb0, rb1, cb, cA, cB; float sa, sb, sA, sB; unsigned xa, xb2, xA, xB;
;         P7C_LOADA(ra0, ra1, ca, sa, xa, gwl);
;         P7C_LOADA(rb0, rb1, cb, sb, xb2, gwl + stride);
;         P7C_ISSUE(GA, ra0, ra1); cA = ca; sA = sa; xA = xa;
; #pragma unroll 1
;         for (int t = gwl; t < NT_TOK; t += 2 * stride) {
;             P7C_LOADA(ra0, ra1, ca, sa, xa, t + 2 * stride); P7C_ISSUE(GB, rb0, rb1); cB = cb; sB = sb; xB = xb2; P7C_COMP(GA, cA, sA, xA, t);
.Lp7c_sk2_b:
	v_mad_u32_u16 v66, v67, s58, v200 op_sel:[1,0,0,0]
	global_load_dwordx4 v[88:91], v64, s[56:57]
	global_load_dwordx4 v[92:95], v66, s[56:57]
	s_setprio 0
	v_mov_b32_dpp v230, v152 row_ror:8 row_mask:0xf bank_mask:0xf
	v_cndmask_b32_e64 v220, v230, v152, s[40:41]
	v_cndmask_b32_e64 v224, v152, v230, s[40:41]
	v_mov_b32_dpp v230, v153 row_ror:8 row_mask:0xf bank_mask:0xf
	v_cndmask_b32_e64 v221, v230, v153, s[40:41]
	v_cndmask_b32_e64 v225, v153, v230, s[40:41]
	v_mov_b32_dpp v230, v154 row_ror:8 row_mask:0xf bank_mask:0xf
	v_cndmask_b32_e64 v222, v230, v154, s[40:41]
	v_cndmask_b32_e64 v226, v154, v230, s[40:41]
	v_mov_b32_dpp v230, v155 row_ror:8 row_mask:0xf bank_mask:0xf
	v_cndmask_b32_e64 v223, v230, v155, s[40:41]
	v_cndmask_b32_e64 v227, v155, v230, s[40:41]
	s_waitcnt vmcnt(33)
	ds_write_b128 v208, v[48:51]
	ds_write_b128 v209, v[52:55] offset:1024
	ds_write_b128 v210, v[68:71] offset:2048
	ds_write_b128 v211, v[72:75] offset:3072
	ds_read_b64_tr_b8 v[240:241], v212
	ds_read_b64_tr_b8 v[242:243], v213
	ds_read_b64_tr_b8 v[244:245], v214
	ds_read_b64_tr_b8 v[246:247], v215
	ds_read_b64_tr_b8 v[248:249], v216
	ds_read_b64_tr_b8 v[250:251], v217
	ds_read_b64_tr_b8 v[252:253], v218
	ds_read_b64_tr_b8 v[228:229], v219
	s_waitcnt lgkmcnt(4)
	s_waitcnt vmcnt(29)
	ds_write_b128 v208, v[32:35] offset:4096
	ds_write_b128 v209, v[36:39] offset:5120
	ds_write_b128 v210, v[56:59] offset:6144
	ds_write_b128 v211, v[60:63] offset:7168
	ds_read_b64_tr_b8 v[48:49], v212 offset:4096
	ds_read_b64_tr_b8 v[50:51], v213 offset:4096
	ds_read_b64_tr_b8 v[52:53], v214 offset:4096
	ds_read_b64_tr_b8 v[54:55], v215 offset:4096
	v_dot4_i32_i8 v232, v240, v220, 0
	v_dot4_i32_i8 v233, v242, v220, 0
	v_dot4_i32_i8 v234, v244, v220, 0
	v_dot4_i32_i8 v235, v246, v220, 0
	v_dot4_i32_i8 v232, v241, v224, v232
	v_dot4_i32_i8 v233, v243, v224, v233
	v_dot4_i32_i8 v234, v245, v224, v234
	v_dot4_i32_i8 v235, v247, v224, v235
	s_waitcnt lgkmcnt(8)
	ds_read_b64_tr_b8 v[240:241], v216 offset:4096
	ds_read_b64_tr_b8 v[242:243], v217 offset:4096
	ds_read_b64_tr_b8 v[244:245], v218 offset:4096
	ds_read_b64_tr_b8 v[246:247], v219 offset:4096
	v_dot4_i32_i8 v236, v248, v220, 0
	v_dot4_i32_i8 v237, v250, v220, 0
	v_dot4_i32_i8 v238, v252, v220, 0
	v_dot4_i32_i8 v239, v228, v220, 0
	v_dot4_i32_i8 v236, v249, v224, v236
	v_dot4_i32_i8 v237, v251, v224, v237
	v_dot4_i32_i8 v238, v253, v224, v238
	v_dot4_i32_i8 v239, v229, v224, v239
	s_waitcnt lgkmcnt(4)
	s_waitcnt vmcnt(25)
	ds_write_b128 v208, v[16:19] offset:8192
	ds_write_b128 v209, v[20:23] offset:9216
	ds_write_b128 v210, v[40:43] offset:10240
	ds_write_b128 v211, v[44:47] offset:11264
	ds_read_b64_tr_b8 v[248:249], v212 offset:8192
	ds_read_b64_tr_b8 v[250:251], v213 offset:8192
	ds_read_b64_tr_b8 v[252:253], v214 offset:8192
	ds_read_b64_tr_b8 v[228:229], v215 offset:8192
	v_dot4_i32_i8 v232, v48, v221, v232
	v_dot4_i32_i8 v233, v50, v221, v233
	v_dot4_i32_i8 v234, v52, v221, v234
	v_dot4_i32_i8 v235, v54, v221, v235
	v_dot4_i32_i8 v232, v49, v225, v232
	v_dot4_i32_i8 v233, v51, v225, v233
	v_dot4_i32_i8 v234, v53, v225, v234
	v_dot4_i32_i8 v235, v55, v225, v235
	s_waitcnt lgkmcnt(8)
	ds_read_b64_tr_b8 v[48:49], v216 offset:8192
	ds_read_b64_tr_b8 v[50:51], v217 offset:8192
	ds_read_b64_tr_b8 v[52:53], v218 offset:8192
	ds_read_b64_tr_b8 v[54:55], v219 offset:8192
	v_dot4_i32_i8 v236, v240, v221, v236
	v_dot4_i32_i8 v237, v242, v221, v237
	v_dot4_i32_i8 v238, v244, v221, v238
	v_dot4_i32_i8 v239, v246, v221, v239
	v_dot4_i32_i8 v236, v241, v225, v236
	v_dot4_i32_i8 v237, v243, v225, v237
	v_dot4_i32_i8 v238, v245, v225, v238
	v_dot4_i32_i8 v239, v247, v225, v239
	s_waitcnt lgkmcnt(4)
	s_waitcnt vmcnt(21)
	ds_write_b128 v208, v[8:11] offset:12288
	ds_write_b128 v209, v[12:15] offset:13312
	ds_write_b128 v210, v[24:27] offset:14336
	ds_write_b128 v211, v[28:31] offset:15360
	ds_read_b64_tr_b8 v[240:241], v212 offset:12288
	ds_read_b64_tr_b8 v[242:243], v213 offset:12288
	ds_read_b64_tr_b8 v[244:245], v214 offset:12288
	ds_read_b64_tr_b8 v[246:247], v215 offset:12288
	v_dot4_i32_i8 v232, v248, v222, v232
	v_dot4_i32_i8 v233, v250, v222, v233
	v_dot4_i32_i8 v234, v252, v222, v234
	v_dot4_i32_i8 v235, v228, v222, v235
	v_dot4_i32_i8 v232, v249, v226, v232
	v_dot4_i32_i8 v233, v251, v226, v233
	v_dot4_i32_i8 v234, v253, v226, v234
	v_dot4_i32_i8 v235, v229, v226, v235
	s_waitcnt lgkmcnt(8)
	ds_read_b64_tr_b8 v[248:249], v216 offset:12288
	ds_read_b64_tr_b8 v[250:251], v217 offset:12288
	ds_read_b64_tr_b8 v[252:253], v218 offset:12288
	ds_read_b64_tr_b8 v[228:229], v219 offset:12288
	v_dot4_i32_i8 v236, v48, v222, v236
	v_dot4_i32_i8 v237, v50, v222, v237
	v_dot4_i32_i8 v238, v52, v222, v238
	v_dot4_i32_i8 v239, v54, v222, v239
	v_dot4_i32_i8 v236, v49, v226, v236
	v_dot4_i32_i8 v237, v51, v226, v237
	v_dot4_i32_i8 v238, v53, v226, v238
	v_dot4_i32_i8 v239, v55, v226, v239
	s_waitcnt lgkmcnt(4)
	v_dot4_i32_i8 v232, v240, v223, v232
	v_dot4_i32_i8 v233, v242, v223, v233
	v_dot4_i32_i8 v234, v244, v223, v234
	v_dot4_i32_i8 v235, v246, v223, v235
	v_dot4_i32_i8 v232, v241, v227, v232
	v_dot4_i32_i8 v233, v243, v227, v233
	v_dot4_i32_i8 v234, v245, v227, v234
	v_dot4_i32_i8 v235, v247, v227, v235
	s_waitcnt lgkmcnt(0)
	v_dot4_i32_i8 v236, v248, v223, v236
	v_dot4_i32_i8 v237, v250, v223, v237
	v_dot4_i32_i8 v238, v252, v223, v238
	v_dot4_i32_i8 v239, v228, v223, v239
	v_dot4_i32_i8 v236, v249, v227, v236
	v_dot4_i32_i8 v237, v251, v227, v237
	v_dot4_i32_i8 v238, v253, v227, v238
	v_dot4_i32_i8 v239, v229, v227, v239
	v_mov_b32_e32 v204, v206
	v_mov_b32_e32 v205, v207
	s_add_i32 s18, s24, s20
	s_min_i32 s18, s18, 0x5fff
	s_ashr_i32 s19, s18, 31
	s_lshl_b64 s[28:29], s[18:19], 8
	s_waitcnt lgkmcnt(0)
; #define P7C_LOADA(R0, R1, C, S, X, t) do { const int tt_ = (t) < NT_TOK ? (t) : NT_TOK - 1; const unsigned char* rp_ = rp0 + (size_t)tt_ * 256; R0 = *(const v4u*)rp_; R1 = *(const v4u*)(rp_ + 16); \
;             C = *(const v4u*)(cp0 + (size_t)tt_ * 128); S = SCQ[tt_]; X = *(const unsigned*)(X2Bw + (size_t)tt_ * DM + 128 * hs + 16 * seg + 2 * r); } while (0)
; #define P7C_ISSUE(G, R0, R1) do { __builtin_amdgcn_s_setprio(3); _Pragma("unroll") for (int i_ = 0; i_ < 16; ++i_) { const unsigned e_ = P7_EID(R0, R1, i_); G[i_] = *(const v4u*)(Vb + (size_t)e_ * 128); } __builtin_amdgcn_s_setprio(0); } while (0)
; __device__ __forceinline__ void p7c_vaxpy(Frame& F, unsigned* bar, unsigned x, unsigned rank) {
;     ...
;         v4u GA[16], GB[16], ra0, ra1, ca, rb0, rb1, cb, cA, cB; float sa, sb, sA, sB; unsigned xa, xb2, xA, xB;
;         P7C_LOADA(ra0, ra1, ca, sa, xa, gwl);
;         P7C_LOADA(rb0, rb1, cb, sb, xb2, gwl + stride);
;         P7C_ISSUE(GA, ra0, ra1); cA = ca; sA = sa; xA = xa;
; #pragma unroll 1
;         for (int t = gwl; t < NT_TOK; t += 2 * stride) {
;             P7C_LOADA(ra0, ra1, ca, sa, xa, t + 2 * stride); P7C_ISSUE(GB, rb0, rb1); cB = cb; sB = sb; xB = xb2; P7C_COMP(GA, cA, sA, xA, t);
;             P7C_LOADA(rb0, rb1, cb, sb, xb2, t + 3 * stride); P7C_ISSUE(GA, ra0, ra1); cA = ca; sA = sa; xA = xa; P7C_COMP(GB, cB, sB, xB, t + stride);
	v_lshl_add_u64 v[8:9], v[158:159], 0, s[28:29]
	s_lshl_b64 s[28:29], s[18:19], 7
	global_load_dwordx4 v[64:67], v[8:9], off offset:16
	global_load_dwordx4 v[76:79], v[8:9], off
	v_lshl_add_u64 v[8:9], v[160:161], 0, s[28:29]
	s_lshl_b64 s[28:29], s[18:19], 2
	s_add_u32 s28, s54, s28
	s_addc_u32 s29, s55, s29
	s_lshl_b64 s[18:19], s[18:19], 12
	v_lshl_add_u64 v[10:11], v[182:183], 0, s[18:19]
	global_load_dwordx4 v[152:155], v[8:9], off
	global_load_dword v207, v157, s[28:29]
	global_load_dword v206, v[10:11], off
	s_setprio 3
	s_waitcnt vmcnt(24)
	v_permlane32_swap_b32_e32 v232, v236
	v_permlane32_swap_b32_e32 v233, v237
	v_mad_u32_u16 v8, v148, s58, v200 op_sel:[0,0,0,0]
	v_permlane32_swap_b32_e32 v234, v238
	v_permlane32_swap_b32_e32 v235, v239
	v_mad_u32_u16 v10, v148, s58, v200 op_sel:[1,0,0,0]
	v_add_u32_e32 v232, v232, v236
	global_load_dwordx4 v[48:51], v8, s[56:57]
	v_add_u32_e32 v233, v233, v237
	global_load_dwordx4 v[52:55], v10, s[56:57]
	v_add_u32_e32 v234, v234, v238
	v_add_u32_e32 v235, v235, v239
	v_mad_u32_u16 v8, v149, s58, v200 op_sel:[0,0,0,0]
	s_nop 1
	v_permlane16_swap_b32_e32 v232, v234
	v_mad_u32_u16 v10, v149, s58, v200 op_sel:[1,0,0,0]
	v_permlane16_swap_b32_e32 v233, v235
	global_load_dwordx4 v[68:71], v8, s[56:57]
	v_add_u32_e32 v232, v232, v234
	global_load_dwordx4 v[72:75], v10, s[56:57]
	v_add_u32_e32 v233, v233, v235
	s_nop 1
	v_mad_u32_u16 v8, v150, s58, v200 op_sel:[0,0,0,0]
	v_mov_b32_dpp v234, v232 quad_perm:[1,0,3,2] row_mask:0xf bank_mask:0xf
	v_mov_b32_dpp v235, v233 quad_perm:[1,0,3,2] row_mask:0xf bank_mask:0xf
	v_mad_u32_u16 v10, v150, s58, v200 op_sel:[1,0,0,0]
	v_cndmask_b32_e64 v236, v235, v232, s[44:45]
	global_load_dwordx4 v[32:35], v8, s[56:57]
	v_cndmask_b32_e64 v237, v233, v234, s[44:45]
	global_load_dwordx4 v[36:39], v10, s[56:57]
	v_cvt_f32_i32_e32 v236, v236
	v_cvt_f32_i32_e32 v237, v237
	v_mad_u32_u16 v8, v151, s58, v200 op_sel:[0,0,0,0]
	v_lshlrev_b32_e32 v238, 16, v204
	v_and_b32_e32 v239, 0xffff0000, v204
	v_mad_u32_u16 v10, v151, s58, v200 op_sel:[1,0,0,0]
	v_fmac_f32_e32 v238, v205, v236
	global_load_dwordx4 v[56:59], v8, s[56:57]
	v_fmac_f32_e32 v239, v205, v237
	global_load_dwordx4 v[60:63], v10, s[56:57]
	v_mul_f32_e32 v240, v239, v239
	v_fmac_f32_e32 v240, v238, v238
	v_mad_u32_u16 v8, v144, s58, v200 op_sel:[0,0,0,0]
	v_cvt_pk_bf16_f32 v244, v238, v239
	global_store_dword v[188:189], v244, off
	v_mad_u32_u16 v10, v144, s58, v200 op_sel:[1,0,0,0]
	s_nop 1
	global_load_dwordx4 v[16:19], v8, s[56:57]
	v_add_f32_dpp v240, v240, v240 quad_perm:[1,0,3,2] row_mask:0xf bank_mask:0xf
	global_load_dwordx4 v[20:23], v10, s[56:57]
	s_nop 1
	v_add_f32_dpp v240, v240, v240 quad_perm:[2,3,0,1] row_mask:0xf bank_mask:0xf
	v_mad_u32_u16 v8, v145, s58, v200 op_sel:[0,0,0,0]
	s_nop 1
	v_add_f32_dpp v240, v240, v240 row_half_mirror row_mask:0xf bank_mask:0xf
	v_mad_u32_u16 v10, v145, s58, v200 op_sel:[1,0,0,0]
	s_nop 1
	global_load_dwordx4 v[40:43], v8, s[56:57]
	v_add_f32_dpp v240, v240, v240 row_mirror row_mask:0xf bank_mask:0xf
	global_load_dwordx4 v[44:47], v10, s[56:57]
	v_mov_b32_e32 v242, v240
	s_nop 1
	v_mad_u32_u16 v8, v146, s58, v200 op_sel:[0,0,0,0]
	v_permlane16_swap_b32_e32 v240, v242
	v_add_f32_e32 v240, v240, v242
	v_mad_u32_u16 v12, v146, s58, v200 op_sel:[1,0,0,0]
	v_mov_b32_e32 v242, v240
	s_nop 1
	v_mad_u32_u16 v24, v147, s58, v200 op_sel:[0,0,0,0]
	v_permlane32_swap_b32_e32 v240, v242
	v_add_f32_e32 v240, v240, v242
	v_mad_u32_u16 v28, v147, s58, v200 op_sel:[1,0,0,0]
	s_and_saveexec_b64 s[18:19], s[42:43]
	global_store_dword v[186:187], v240, off
	s_mov_b64 exec, s[18:19]
	global_load_dwordx4 v[8:11], v8, s[56:57]
	s_nop 0
	global_load_dwordx4 v[12:15], v12, s[56:57]
	s_nop 0
	global_load_dwordx4 v[24:27], v24, s[56:57]
	s_nop 0
	global_load_dwordx4 v[28:31], v28, s[56:57]
	s_setprio 0
	v_mov_b32_dpp v230, v4 row_ror:8 row_mask:0xf bank_mask:0xf
	v_cndmask_b32_e64 v220, v230, v4, s[40:41]
	v_cndmask_b32_e64 v224, v4, v230, s[40:41]
	v_mov_b32_dpp v230, v5 row_ror:8 row_mask:0xf bank_mask:0xf
	v_cndmask_b32_e64 v221, v230, v5, s[40:41]
	v_cndmask_b32_e64 v225, v5, v230, s[40:41]
	v_mov_b32_dpp v230, v6 row_ror:8 row_mask:0xf bank_mask:0xf
	v_cndmask_b32_e64 v222, v230, v6, s[40:41]
	v_cndmask_b32_e64 v226, v6, v230, s[40:41]
	v_mov_b32_dpp v230, v7 row_ror:8 row_mask:0xf bank_mask:0xf
	v_cndmask_b32_e64 v223, v230, v7, s[40:41]
	v_cndmask_b32_e64 v227, v7, v230, s[40:41]
	s_waitcnt vmcnt(34)
	ds_write_b128 v208, v[128:131]
	ds_write_b128 v209, v[132:135] offset:1024
	ds_write_b128 v210, v[136:139] offset:2048
	ds_write_b128 v211, v[140:143] offset:3072
	ds_read_b64_tr_b8 v[240:241], v212
	ds_read_b64_tr_b8 v[242:243], v213
	ds_read_b64_tr_b8 v[244:245], v214
	ds_read_b64_tr_b8 v[246:247], v215
	ds_read_b64_tr_b8 v[248:249], v216
	ds_read_b64_tr_b8 v[250:251], v217
	ds_read_b64_tr_b8 v[252:253], v218
	ds_read_b64_tr_b8 v[228:229], v219
	s_waitcnt lgkmcnt(4)
	s_waitcnt vmcnt(30)
	ds_write_b128 v208, v[112:115] offset:4096
	ds_write_b128 v209, v[116:119] offset:5120
	ds_write_b128 v210, v[120:123] offset:6144
	ds_write_b128 v211, v[124:127] offset:7168
	ds_read_b64_tr_b8 v[128:129], v212 offset:4096
	ds_read_b64_tr_b8 v[130:131], v213 offset:4096
	ds_read_b64_tr_b8 v[132:133], v214 offset:4096
	ds_read_b64_tr_b8 v[134:135], v215 offset:4096
	v_dot4_i32_i8 v232, v240, v220, 0
	v_dot4_i32_i8 v233, v242, v220, 0
	v_dot4_i32_i8 v234, v244, v220, 0
	v_dot4_i32_i8 v235, v246, v220, 0
	v_dot4_i32_i8 v232, v241, v224, v232
	v_dot4_i32_i8 v233, v243, v224, v233
	v_dot4_i32_i8 v234, v245, v224, v234
	v_dot4_i32_i8 v235, v247, v224, v235
	s_waitcnt lgkmcnt(8)
; #define P7C_LOADA(R0, R1, C, S, X, t) do { const int tt_ = (t) < NT_TOK ? (t) : NT_TOK - 1; const unsigned char* rp_ = rp0 + (size_t)tt_ * 256; R0 = *(const v4u*)rp_; R1 = *(const v4u*)(rp_ + 16); \
;             C = *(const v4u*)(cp0 + (size_t)tt_ * 128); S = SCQ[tt_]; X = *(const unsigned*)(X2Bw + (size_t)tt_ * DM + 128 * hs + 16 * seg + 2 * r); } while (0)
; #define P7C_ISSUE(G, R0, R1) do { __builtin_amdgcn_s_setprio(3); _Pragma("unroll") for (int i_ = 0; i_ < 16; ++i_) { const unsigned e_ = P7_EID(R0, R1, i_); G[i_] = *(const v4u*)(Vb + (size_t)e_ * 128); } __builtin_amdgcn_s_setprio(0); } while (0)
; __device__ __forceinline__ void xcd_barrier(const XcdBarrier& b) {
;     asm volatile("s_waitcnt vmcnt(0)" ::: "memory");
;     __syncthreads();
;     if (threadIdx.x == 0) {
;         unsigned* bar = b.bar;
;         __builtin_amdgcn_s_waitcnt(0);
;         unsigned nloc = b.st[0], nx = b.st[1];
;         if (nloc == 0u) { xcd_barrier_complete(bar, b.x, nloc, nx); b.st[0] = nloc; b.st[1] = nx; }
; __device__ __forceinline__ void p7c_vaxpy(Frame& F, unsigned* bar, unsigned x, unsigned rank) {
;     ...
;         v4u GA[16], GB[16], ra0, ra1, ca, rb0, rb1, cb, cA, cB; float sa, sb, sA, sB; unsigned xa, xb2, xA, xB;
;         P7C_LOADA(ra0, ra1, ca, sa, xa, gwl);
;         P7C_LOADA(rb0, rb1, cb, sb, xb2, gwl + stride);
;         P7C_ISSUE(GA, ra0, ra1); cA = ca; sA = sa; xA = xa;
; #pragma unroll 1
;         for (int t = gwl; t < NT_TOK; t += 2 * stride) {
;             P7C_LOADA(ra0, ra1, ca, sa, xa, t + 2 * stride); P7C_ISSUE(GB, rb0, rb1); cB = cb; sB = sb; xB = xb2; P7C_COMP(GA, cA, sA, xA, t);
;             P7C_LOADA(rb0, rb1, cb, sb, xb2, t + 3 * stride); P7C_ISSUE(GA, ra0, ra1); cA = ca; sA = sa; xA = xa; P7C_COMP(GB, cB, sB, xB, t + stride);
	ds_read_b64_tr_b8 v[240:241], v216 offset:4096
	ds_read_b64_tr_b8 v[242:243], v217 offset:4096
	ds_read_b64_tr_b8 v[244:245], v218 offset:4096
	ds_read_b64_tr_b8 v[246:247], v219 offset:4096
	v_dot4_i32_i8 v236, v248, v220, 0
	v_dot4_i32_i8 v237, v250, v220, 0
	v_dot4_i32_i8 v238, v252, v220, 0
	v_dot4_i32_i8 v239, v228, v220, 0
	v_dot4_i32_i8 v236, v249, v224, v236
	v_dot4_i32_i8 v237, v251, v224, v237
	v_dot4_i32_i8 v238, v253, v224, v238
	v_dot4_i32_i8 v239, v229, v224, v239
	s_waitcnt lgkmcnt(4)
	s_waitcnt vmcnt(26)
	ds_write_b128 v208, v[96:99] offset:8192
	ds_write_b128 v209, v[100:103] offset:9216
	ds_write_b128 v210, v[104:107] offset:10240
	ds_write_b128 v211, v[108:111] offset:11264
	ds_read_b64_tr_b8 v[248:249], v212 offset:8192
	ds_read_b64_tr_b8 v[250:251], v213 offset:8192
	ds_read_b64_tr_b8 v[252:253], v214 offset:8192
	ds_read_b64_tr_b8 v[228:229], v215 offset:8192
	v_dot4_i32_i8 v232, v128, v221, v232
	v_dot4_i32_i8 v233, v130, v221, v233
	v_dot4_i32_i8 v234, v132, v221, v234
	v_dot4_i32_i8 v235, v134, v221, v235
	v_dot4_i32_i8 v232, v129, v225, v232
	v_dot4_i32_i8 v233, v131, v225, v233
	v_dot4_i32_i8 v234, v133, v225, v234
	v_dot4_i32_i8 v235, v135, v225, v235
	s_waitcnt lgkmcnt(8)
	ds_read_b64_tr_b8 v[128:129], v216 offset:8192
	ds_read_b64_tr_b8 v[130:131], v217 offset:8192
	ds_read_b64_tr_b8 v[132:133], v218 offset:8192
	ds_read_b64_tr_b8 v[134:135], v219 offset:8192
	v_dot4_i32_i8 v236, v240, v221, v236
	v_dot4_i32_i8 v237, v242, v221, v237
	v_dot4_i32_i8 v238, v244, v221, v238
	v_dot4_i32_i8 v239, v246, v221, v239
	v_dot4_i32_i8 v236, v241, v225, v236
	v_dot4_i32_i8 v237, v243, v225, v237
	v_dot4_i32_i8 v238, v245, v225, v238
	v_dot4_i32_i8 v239, v247, v225, v239
	s_waitcnt lgkmcnt(4)
	s_waitcnt vmcnt(22)
	ds_write_b128 v208, v[80:83] offset:12288
	ds_write_b128 v209, v[84:87] offset:13312
	ds_write_b128 v210, v[88:91] offset:14336
	ds_write_b128 v211, v[92:95] offset:15360
	ds_read_b64_tr_b8 v[240:241], v212 offset:12288
	ds_read_b64_tr_b8 v[242:243], v213 offset:12288
	ds_read_b64_tr_b8 v[244:245], v214 offset:12288
	ds_read_b64_tr_b8 v[246:247], v215 offset:12288
	v_dot4_i32_i8 v232, v248, v222, v232
	v_dot4_i32_i8 v233, v250, v222, v233
	v_dot4_i32_i8 v234, v252, v222, v234
	v_dot4_i32_i8 v235, v228, v222, v235
	v_dot4_i32_i8 v232, v249, v226, v232
	v_dot4_i32_i8 v233, v251, v226, v233
	v_dot4_i32_i8 v234, v253, v226, v234
	v_dot4_i32_i8 v235, v229, v226, v235
	s_waitcnt lgkmcnt(8)
	ds_read_b64_tr_b8 v[248:249], v216 offset:12288
	ds_read_b64_tr_b8 v[250:251], v217 offset:12288
	ds_read_b64_tr_b8 v[252:253], v218 offset:12288
	ds_read_b64_tr_b8 v[228:229], v219 offset:12288
	v_dot4_i32_i8 v236, v128, v222, v236
	v_dot4_i32_i8 v237, v130, v222, v237
	v_dot4_i32_i8 v238, v132, v222, v238
	v_dot4_i32_i8 v239, v134, v222, v239
	v_dot4_i32_i8 v236, v129, v226, v236
	v_dot4_i32_i8 v237, v131, v226, v237
	v_dot4_i32_i8 v238, v133, v226, v238
	v_dot4_i32_i8 v239, v135, v226, v239
	s_waitcnt lgkmcnt(4)
	v_dot4_i32_i8 v232, v240, v223, v232
	v_dot4_i32_i8 v233, v242, v223, v233
	v_dot4_i32_i8 v234, v244, v223, v234
	v_dot4_i32_i8 v235, v246, v223, v235
	v_dot4_i32_i8 v232, v241, v227, v232
	v_dot4_i32_i8 v233, v243, v227, v233
	v_dot4_i32_i8 v234, v245, v227, v234
	v_dot4_i32_i8 v235, v247, v227, v235
	s_waitcnt lgkmcnt(0)
	v_dot4_i32_i8 v236, v248, v223, v236
	v_dot4_i32_i8 v237, v250, v223, v237
	v_dot4_i32_i8 v238, v252, v223, v238
	v_dot4_i32_i8 v239, v228, v223, v239
	v_dot4_i32_i8 v236, v249, v227, v236
	v_dot4_i32_i8 v237, v251, v227, v237
	v_dot4_i32_i8 v238, v253, v227, v238
	v_dot4_i32_i8 v239, v229, v227, v239
	v_mov_b32_e32 v204, v199
	v_mov_b32_e32 v205, v198
	s_add_i32 s98, s23, s20
	s_branch .LBB0_1088
.Lp7c_drain:
	s_nop 2
	v_permlane32_swap_b32_e32 v232, v236
	v_permlane32_swap_b32_e32 v233, v237
	v_permlane32_swap_b32_e32 v234, v238
	v_permlane32_swap_b32_e32 v235, v239
	v_add_u32_e32 v232, v232, v236
	v_add_u32_e32 v233, v233, v237
	v_add_u32_e32 v234, v234, v238
	v_add_u32_e32 v235, v235, v239
	s_nop 1
	v_permlane16_swap_b32_e32 v232, v234
	v_permlane16_swap_b32_e32 v233, v235
	v_add_u32_e32 v232, v232, v234
	v_add_u32_e32 v233, v233, v235
	s_nop 1
	v_mov_b32_dpp v234, v232 quad_perm:[1,0,3,2] row_mask:0xf bank_mask:0xf
	v_mov_b32_dpp v235, v233 quad_perm:[1,0,3,2] row_mask:0xf bank_mask:0xf
	v_cndmask_b32_e64 v236, v235, v232, s[44:45]
	v_cndmask_b32_e64 v237, v233, v234, s[44:45]
	v_cvt_f32_i32_e32 v236, v236
	v_cvt_f32_i32_e32 v237, v237
	v_lshlrev_b32_e32 v238, 16, v204
	v_and_b32_e32 v239, 0xffff0000, v204
	v_fmac_f32_e32 v238, v205, v236
	v_fmac_f32_e32 v239, v205, v237
	v_mul_f32_e32 v240, v239, v239
	v_fmac_f32_e32 v240, v238, v238
	v_cvt_pk_bf16_f32 v244, v238, v239
	s_cmpk_gt_i32 s98, 0x5fff
	s_cbranch_scc1 .Lp7c_sk1_d
	s_ashr_i32 s99, s98, 31
	s_lshl_b64 s[100:101], s[98:99], 12
	v_lshl_add_u64 v[242:243], v[182:183], 0, s[100:101]
	global_store_dword v[242:243], v244, off
.Lp7c_sk1_d:
	s_nop 1
	v_add_f32_dpp v240, v240, v240 quad_perm:[1,0,3,2] row_mask:0xf bank_mask:0xf
	s_nop 1
	v_add_f32_dpp v240, v240, v240 quad_perm:[2,3,0,1] row_mask:0xf bank_mask:0xf
	s_nop 1
	v_add_f32_dpp v240, v240, v240 row_half_mirror row_mask:0xf bank_mask:0xf
	s_nop 1
	v_add_f32_dpp v240, v240, v240 row_mirror row_mask:0xf bank_mask:0xf
	v_mov_b32_e32 v242, v240
	s_nop 1
	v_permlane16_swap_b32_e32 v240, v242
	v_add_f32_e32 v240, v240, v242
	v_mov_b32_e32 v242, v240
	s_nop 1
	v_permlane32_swap_b32_e32 v240, v242
	v_add_f32_e32 v240, v240, v242
	s_cmpk_gt_i32 s98, 0x5fff
	s_cbranch_scc1 .Lp7c_sk2_d
	s_ashr_i32 s99, s98, 31
	s_lshl_b64 s[100:101], s[98:99], 6
	v_lshl_add_u64 v[242:243], v[184:185], 0, s[100:101]
	s_and_saveexec_b64 s[18:19], s[42:43]
	global_store_dword v[242:243], v240, off
	s_mov_b64 exec, s[18:19]
.Lp7c_sk2_d:
	s_branch .LBB0_1083
.LBB0_1094:
	s_waitcnt vmcnt(0)
	s_barrier
	s_mov_b64 s[0:1], exec
	v_readlane_b32 s2, v254, 5
	v_readlane_b32 s3, v254, 6
	s_and_b64 s[2:3], s[0:1], s[2:3]
	s_mov_b64 exec, s[2:3]
	s_cbranch_execz .LBB0_1146
	s_add_i32 s2, 0, 0x20160
	s_waitcnt vmcnt(23)
	v_mov_b32_e32 v0, s2
	s_waitcnt vmcnt(0) expcnt(0) lgkmcnt(0)
	ds_read_b32 v2, v0
	s_add_i32 s2, 0, 0x20164
	v_mov_b32_e32 v0, s2
	ds_read_b32 v0, v0
	s_waitcnt lgkmcnt(1)
	v_cmp_ne_u32_e32 vcc, 0, v2
	s_cbranch_vccnz .LBB0_1110
	v_readlane_b32 s4, v254, 0
	v_readlane_b32 s5, v254, 1
	s_load_dwordx2 s[2:3], s[4:5], 0x4
	s_mov_b32 s8, 1
	v_mov_b32_e32 v16, 0
	s_waitcnt lgkmcnt(0)
	s_mul_i32 s9, s2, s68
	s_mul_i32 s9, s9, s3
	s_branch .LBB0_1098
